# dense attention B: K tiles loaded HBM->LDS directly into an unpadded XOR-swizzled image (no K staging registers / ds_write)
# baseline (speedup 1.0000x reference)
; template <int DQK, bool FIXEDM>
; DI void attn_dense_mfma(const bf16_t* Qb, int ldq, const bf16_t* Kb, int ldk, const bf16_t* Vb, int ldv, bf16_t* gate_io, char* smem, bool store, float mbound) {
;     ...
;   const int tid = otid(), lane = tid & 63, wid = tid >> 6, r = lane & 31, h = lane >> 5;
;   bf16x8 qf[NS];
; #pragma unroll
;   for (int s = 0; s < NS; ++s) qf[s] = *(const bf16x8*)(Qb + (size_t)(wid * 32 + r) * ldq + 16 * s + 8 * h);
;   const bf16_t* kp = Kb + (size_t)(tid >> 2) * ldk + (tid & 3) * (NKC * 8);
;   const int kso = ((tid >> 2) * KLD + (tid & 3) * (NKC * 8)) * 2;
;   const bf16_t* vp0 = Vb + (size_t)(tid >> 3) * ldv + (tid & 7) * 8;
;   const bf16_t* vp1 = vp0 + (size_t)32 * ldv;
;   const int vso = ((tid >> 3) * VLD + (tid & 7) * 8) * 2;
;   const size_t kstep = (size_t)64 * ldk, vstep = (size_t)64 * ldv;
;   u32x4 rk[NKC], rv[2];
;     ...
;   const unsigned vb0 = (unsigned)(size_t)sVc + (unsigned)(((4 * h + ((lane & 15) >> 2)) * VLD + 16 * ((lane >> 4) & 1) + 4 * (lane & 3)) * 2);
;   f32x16 o0 = splat16(0.f), o1 = splat16(0.f), negm = splat16(FIXEDM ? -mbound : 0.f);
;   f32x16 pa0, pa1, pc0, pc1;
;   float m_run = 0.f, l_run = 0.f;
;   constexpr int NT = SEQ / 64;
;   __syncthreads();
;   KLOAD(); VLOAD(); KSTORE(0); VSTORE(0);
;   KLOAD(); KSTORE(1);
;   __syncthreads();
;   QKT(pa0, pa1, 0);
; DI void dense_item(const Params& p, int l, int combo, int qblk, char* smem, bool store) {
;   const int br = combo >> 4, bh = combo & 15, b = bh >> 2, h = bh & 3;
;   const size_t t0 = (size_t)b * SEQ + qblk * 128;
;   bf16_t* gate_io = P_PROJ + t0 * PW + C_GATE + br * 256 + h * 64;
;   float bbound = 0.f;
;   if (br != 0) {
;     const int ln = otid() & 63;
;     float gq = fabsf(p.gq_g[l * 64 + ln]), gk = fabsf(p.gk_g[l * 64 + ln]);
; #pragma unroll
;     for (int o = 32; o; o >>= 1) { gq = fmaxf(gq, __shfl_xor(gq, o)); gk = fmaxf(gk, __shfl_xor(gk, o)); }
;     bbound = 64.0f * QS64 * 1.02f * gq * gk + 0.05f;
;   }
;   if (br == 0)
;     attn_dense_mfma<96, false>(P_QA + t0 * 384 + h * 96, 384, P_KA + (size_t)b * SEQ * 384 + h * 96, 384, P_VA + (size_t)b * SEQ * 256 + h * 64, 256, gate_io, smem, store, 0.f);
;   else {
;     if (bbound <= 60.0f) attn_dense_mfma<64, true>(P_PROJ + t0 * PW + C_BQ + h * 64, PW, P_PROJ + (size_t)b * SEQ * PW + C_BK + (h >> 1) * 64, PW,
.LBB0_164:
	s_lshr_b32 s0, s29, 5
	s_and_b32 s0, s0, 2
	s_ashr_i32 s1, s29, 7
	s_or_b32 s30, s0, s1
	s_lshl_b32 s0, s30, 3
	v_readlane_b32 s1, v253, 54
	s_or_b32 s1, s0, s1
	s_lshl_b32 s1, s1, 11
	s_and_b32 s1, s1, 0x6000
	s_xor_b32 s34, s1, 0x4000
	s_lshl_b32 s1, s29, 7
	s_and_b32 s1, s1, 0x1f80
	s_or_b32 s35, s34, s1
	s_mul_i32 s31, s35, 0x1300
	s_cmp_lt_u32 s0, 16
	s_mov_b64 s[0:1], -1
	s_cbranch_scc1 .LBB0_187
	v_mov_b32 v0, v188
	v_cmp_lt_i32_e32 vcc, v252, v189
	v_and_or_b32 v0, v0, 63, s28
	v_lshlrev_b32_e32 v0, 2, v0
	global_load_dword v2, v0, s[74:75]
	s_nop 0
	global_load_dword v0, v0, s[44:45]
	v_cndmask_b32_e32 v3, v204, v252, vcc
	v_lshlrev_b32_e32 v3, 2, v3
	v_cmp_lt_i32_e32 vcc, v191, v189
	s_lshl_b32 s0, s31, 1
	v_readlane_b32 s1, v253, 37
	v_cndmask_b32_e32 v4, v204, v191, vcc
	v_lshlrev_b32_e32 v4, 2, v4
	v_cmp_lt_i32_e32 vcc, v192, v189
	s_add_u32 s24, s1, s0
	v_readlane_b32 s0, v253, 38
	v_cndmask_b32_e32 v5, v204, v192, vcc
	v_lshlrev_b32_e32 v5, 2, v5
	v_cmp_lt_i32_e32 vcc, v193, v189
	s_mul_i32 s6, s34, 0x2600
	s_addc_u32 s25, s0, 0
	v_readlane_b32 s0, v255, 2
	s_add_u32 s22, s0, s6
	s_mov_b32 s0, 0x42700000
	s_waitcnt vmcnt(1)
	v_and_b32_e32 v6, 0x7fffffff, v2
	s_waitcnt vmcnt(0)
	v_and_b32_e32 v7, 0x7fffffff, v0
	ds_bpermute_b32 v6, v3, v6
	ds_bpermute_b32 v3, v3, v7
	v_max_f32_e64 v2, |v2|, |v2|
	v_max_f32_e64 v0, |v0|, |v0|
	s_waitcnt lgkmcnt(1)
	v_max_f32_e32 v6, v6, v6
	s_waitcnt lgkmcnt(0)
	v_max_f32_e32 v3, v3, v3
	v_max_f32_e32 v2, v2, v6
	v_max_f32_e32 v0, v0, v3
	ds_bpermute_b32 v3, v4, v2
	ds_bpermute_b32 v4, v4, v0
	v_cndmask_b32_e32 v6, v204, v193, vcc
	v_lshlrev_b32_e32 v6, 2, v6
	v_cmp_lt_i32_e32 vcc, v194, v189
	s_waitcnt lgkmcnt(1)
	v_max_f32_e32 v3, v3, v3
	s_waitcnt lgkmcnt(0)
	v_max_f32_e32 v4, v4, v4
	v_max_f32_e32 v2, v2, v3
	v_max_f32_e32 v0, v0, v4
	ds_bpermute_b32 v3, v5, v2
	ds_bpermute_b32 v4, v5, v0
	v_cndmask_b32_e32 v5, v204, v194, vcc
	v_lshlrev_b32_e32 v5, 2, v5
	v_cmp_lt_i32_e32 vcc, v195, v189
	s_waitcnt lgkmcnt(1)
	v_max_f32_e32 v3, v3, v3
	s_waitcnt lgkmcnt(0)
	v_max_f32_e32 v4, v4, v4
	v_max_f32_e32 v2, v2, v3
	v_max_f32_e32 v0, v0, v4
	ds_bpermute_b32 v3, v6, v2
	ds_bpermute_b32 v4, v6, v0
	v_cndmask_b32_e32 v6, v204, v195, vcc
	s_waitcnt lgkmcnt(1)
	v_max_f32_e32 v3, v3, v3
	s_waitcnt lgkmcnt(0)
	v_max_f32_e32 v4, v4, v4
	v_max_f32_e32 v2, v2, v3
	v_max_f32_e32 v0, v0, v4
	ds_bpermute_b32 v3, v5, v2
	ds_bpermute_b32 v4, v5, v0
	v_lshlrev_b32_e32 v5, 2, v6
	s_waitcnt lgkmcnt(1)
	v_max_f32_e32 v3, v3, v3
	s_waitcnt lgkmcnt(0)
	v_max_f32_e32 v4, v4, v4
	v_max_f32_e32 v2, v2, v3
	v_max_f32_e32 v0, v0, v4
	ds_bpermute_b32 v3, v5, v2
	ds_bpermute_b32 v4, v5, v0
	s_waitcnt lgkmcnt(1)
	v_max_f32_e32 v3, v3, v3
	s_waitcnt lgkmcnt(0)
	v_max_f32_e32 v4, v4, v4
	v_max_f32_e32 v2, v2, v3
	v_max_f32_e32 v0, v0, v4
	v_mul_f32_e32 v2, 0x413c5bb7, v2
	v_fmaak_f32 v35, v2, v0, 0x3d4ccccd
	v_cmp_ge_f32_e32 vcc, s0, v35
	v_readlane_b32 s0, v255, 5
	s_addc_u32 s23, s0, 0
	s_and_saveexec_b64 s[0:1], vcc
	s_xor_b64 s[0:1], exec, s[0:1]
	s_cbranch_execz .LBB0_169
	s_movk_i32 s7, 0x60
	v_and_b32_e32 v197, 31, v188
	v_lshrrev_b32_e32 v0, 1, v188
	v_and_or_b32 v0, v0, s7, v197
	v_mul_u32_u24_e32 v162, 0x1300, v0
	v_mov_b32_e32 v163, 0
	v_bfe_u32 v198, v188, 5, 1
	v_lshlrev_b32_e32 v166, 2, v198
	v_lshlrev_b32_e32 v199, 1, v162
	v_lshl_add_u32 v199, v198, 4, v199
	global_load_dwordx4 v[114:117], v199, s[24:25] offset:0
	global_load_dwordx4 v[118:121], v199, s[24:25] offset:32
	global_load_dwordx4 v[122:125], v199, s[24:25] offset:64
	global_load_dwordx4 v[126:129], v199, s[24:25] offset:96
	s_movk_i32 s7, 0x2600
	v_lshrrev_b32_e32 v0, 6, v188
	v_bfe_u32 v197, v188, 3, 3
	v_lshl_add_u32 v0, v0, 4, v197
	v_mul_lo_u32 v171, v0, s7
	v_add_u32_e32 v172, 0x13000, v171
	v_bfe_u32 v0, v188, 4, 2
	v_and_b32_e32 v197, 7, v188
	v_xor_b32_e32 v0, v0, v197
	v_xor_b32_e32 v197, 4, v0
	v_lshl_add_u32 v171, v0, 4, v171
	v_lshl_add_u32 v172, v197, 4, v172
	v_add_u32_e32 v171, 0x200, v171
	v_add_u32_e32 v172, 0x200, v172
	v_lshrrev_b32_e32 v0, 3, v188
	v_and_b32_e32 v197, 7, v188
	v_mul_lo_u32 v165, v0, s7
	v_lshl_add_u32 v165, v197, 4, v165
	v_mul_u32_u24_e32 v190, 0xc0, v0
	v_lshl_add_u32 v190, v197, 4, v190
	v_add_u32_e32 v190, 0x4800, v190
	v_and_b32_e32 v0, 31, v188
	v_lshlrev_b32_e32 v0, 7, v0
	v_bfe_u32 v197, v188, 1, 3
	v_xor_b32_e32 v191, v198, v197
	v_lshl_add_u32 v191, v191, 4, v0
	v_or_b32_e32 v168, 2, v198
	v_xor_b32_e32 v168, v168, v197
	v_lshl_add_u32 v168, v168, 4, v0
	v_or_b32_e32 v169, 4, v198
	v_xor_b32_e32 v169, v169, v197
	v_lshl_add_u32 v169, v169, 4, v0
	v_or_b32_e32 v170, 6, v198
	v_xor_b32_e32 v170, v170, v197
	v_lshl_add_u32 v170, v170, 4, v0
	v_bfe_u32 v0, v188, 2, 2
	v_lshl_add_u32 v0, v198, 2, v0
	v_mul_u32_u24_e32 v192, 0xc0, v0
	v_bfe_u32 v0, v188, 4, 1
	v_lshl_add_u32 v192, v0, 5, v192
	v_and_b32_e32 v0, 3, v188
	v_lshl_add_u32 v192, v0, 3, v192
	v_add_u32_e32 v192, 0x4800, v192
	s_mov_b32 s26, s22
	s_mov_b32 s27, s23
	s_mov_b32 s36, s22
	s_mov_b32 s37, s23
	s_add_u32 s4, s22, 0x4c000
	s_addc_u32 s5, s23, 0
	v_mov_b32_e32 v18, 0
	v_mov_b32_e32 v19, 0
	v_mov_b32_e32 v20, 0
	v_mov_b32_e32 v21, 0
	v_mov_b32_e32 v22, 0
	v_mov_b32_e32 v23, 0
	v_mov_b32_e32 v24, 0
	v_mov_b32_e32 v25, 0
	v_mov_b32_e32 v26, 0
	v_mov_b32_e32 v27, 0
	v_mov_b32_e32 v28, 0
	v_mov_b32_e32 v29, 0
	v_mov_b32_e32 v30, 0
	v_mov_b32_e32 v31, 0
	v_mov_b32_e32 v32, 0
	v_mov_b32_e32 v33, 0
	v_mov_b32_e32 v2, 0
	v_mov_b32_e32 v3, 0
	v_mov_b32_e32 v4, 0
	v_mov_b32_e32 v5, 0
	v_mov_b32_e32 v6, 0
	v_mov_b32_e32 v7, 0
	v_mov_b32_e32 v8, 0
	v_mov_b32_e32 v9, 0
	v_mov_b32_e32 v10, 0
	v_mov_b32_e32 v11, 0
	v_mov_b32_e32 v12, 0
	v_mov_b32_e32 v13, 0
	v_mov_b32_e32 v14, 0
	v_mov_b32_e32 v15, 0
	v_mov_b32_e32 v16, 0
	v_mov_b32_e32 v17, 0
	v_mov_b32_e32 v193, 0
	v_mov_b32_e32 v194, 0
	v_mov_b32_e32 v195, 0
	v_mov_b32_e32 v196, 0
	v_lshrrev_b32_e32 v0, 6, v188
	v_lshlrev_b32_e32 v0, 11, v0
	s_nop 1
	v_readfirstlane_b32 s7, v0
	s_barrier
; #define KLOAD() do { _Pragma("unroll") for (int i = 0; i < NKC; ++i) rk[i] = *(const u32x4*)(kp + i * 8); kp += kstep; } while (0)
; #define VLOAD() do { rv[0] = *(const u32x4*)vp0; rv[1] = *(const u32x4*)vp1; vp0 += vstep; vp1 += vstep; } while (0)
; #define KSTORE(st) do { _Pragma("unroll") for (int i = 0; i < NKC; ++i) *(u32x4*)(sKc + (st) * KBYTES + kso + i * 16) = rk[i]; } while (0)
; #define VSTORE(st) do { *(u32x4*)(sVc + (st) * VBYTES + vso) = rv[0]; *(u32x4*)(sVc + (st) * VBYTES + vso + 32 * VLD * 2) = rv[1]; } while (0)
; #define QKT(P0, P1, st) do { \
;     const bf16_t* sK = (const bf16_t*)(sKc + (st) * KBYTES) + r * KLD + 8 * h; \
;     P0 = negm; P1 = negm; \
;     _Pragma("unroll") for (int s = 0; s < NS; ++s) { \
;       bf16x8 k0 = *(const bf16x8*)(sK + 16 * s); bf16x8 k1 = *(const bf16x8*)(sK + 32 * KLD + 16 * s); \
;       P0 = MFMA32(k0, qf[s], P0); P1 = MFMA32(k1, qf[s], P1); } } while (0)
; template <int DQK, bool FIXEDM>
; DI void attn_dense_mfma(const bf16_t* Qb, int ldq, const bf16_t* Kb, int ldk, const bf16_t* Vb, int ldv, bf16_t* gate_io, char* smem, bool store, float mbound) {
;     ...
;   __syncthreads();
;   KLOAD(); VLOAD(); KSTORE(0); VSTORE(0);
;   KLOAD(); KSTORE(1);
;   __syncthreads();
;   QKT(pa0, pa1, 0);
;   __syncthreads();
	s_mov_b32 m0, s7
	s_nop 0
	global_load_lds_dwordx4 v171, s[26:27]
	s_add_u32 m0, m0, 0x400
	s_nop 0
	global_load_lds_dwordx4 v172, s[26:27]
	s_add_u32 s26, s26, 0x98000
	s_addc_u32 s27, s27, 0
	global_load_dwordx4 v[176:179], v165, s[36:37] offset:768
	global_load_dwordx4 v[180:183], v165, s[4:5] offset:768
	s_add_u32 s36, s36, 0x98000
	s_addc_u32 s37, s37, 0
	s_add_u32 s4, s4, 0x98000
	s_addc_u32 s5, s5, 0
	s_waitcnt vmcnt(2)
	s_waitcnt vmcnt(1)
	ds_write_b128 v190, v[176:179] offset:0
	s_waitcnt vmcnt(0)
	ds_write_b128 v190, v[180:183] offset:6144
	s_add_u32 m0, m0, 0x2000
	s_nop 0
	global_load_lds_dwordx4 v171, s[26:27]
	s_add_u32 m0, m0, 0x400
	s_nop 0
	global_load_lds_dwordx4 v172, s[26:27]
	s_add_u32 s26, s26, 0x98000
	s_addc_u32 s27, s27, 0
	s_waitcnt vmcnt(0)
	s_waitcnt lgkmcnt(0)
	s_barrier
	ds_read_b128 v[34:37], v191 offset:0
	ds_read_b128 v[38:41], v168 offset:0
	ds_read_b128 v[42:45], v169 offset:0
	ds_read_b128 v[46:49], v170 offset:0
	ds_read_b128 v[130:133], v191 offset:4096
	ds_read_b128 v[134:137], v168 offset:4096
	ds_read_b128 v[138:141], v169 offset:4096
	ds_read_b128 v[142:145], v170 offset:4096
	s_waitcnt lgkmcnt(7)
	v_mfma_f32_32x32x16_bf16 v[50:65], v[34:37], v[114:117], 0
	s_waitcnt lgkmcnt(6)
	v_mfma_f32_32x32x16_bf16 v[50:65], v[38:41], v[118:121], v[50:65]
	s_waitcnt lgkmcnt(5)
	v_mfma_f32_32x32x16_bf16 v[50:65], v[42:45], v[122:125], v[50:65]
	s_waitcnt lgkmcnt(4)
	v_mfma_f32_32x32x16_bf16 v[50:65], v[46:49], v[126:129], v[50:65]
	s_waitcnt lgkmcnt(3)
	v_mfma_f32_32x32x16_bf16 v[66:81], v[130:133], v[114:117], 0
	s_waitcnt lgkmcnt(2)
	v_mfma_f32_32x32x16_bf16 v[66:81], v[134:137], v[118:121], v[66:81]
	s_waitcnt lgkmcnt(1)
	v_mfma_f32_32x32x16_bf16 v[66:81], v[138:141], v[122:125], v[66:81]
	s_waitcnt lgkmcnt(0)
	v_mfma_f32_32x32x16_bf16 v[66:81], v[142:145], v[126:129], v[66:81]
	s_barrier
	s_mov_b32 s7, 0
.Lattnb_loop:
	ds_read_b128 v[34:37], v191 offset:9216
	ds_read_b128 v[38:41], v168 offset:9216
	ds_read_b128 v[42:45], v169 offset:9216
	ds_read_b128 v[46:49], v170 offset:9216
	ds_read_b128 v[130:133], v191 offset:13312
	ds_read_b128 v[134:137], v168 offset:13312
	ds_read_b128 v[138:141], v169 offset:13312
	ds_read_b128 v[142:145], v170 offset:13312
	s_sub_u32 m0, m0, 0x2800
	s_nop 0
	global_load_lds_dwordx4 v171, s[26:27]
	s_add_u32 m0, m0, 0x400
	s_nop 0
	global_load_lds_dwordx4 v172, s[26:27]
	s_add_u32 s26, s26, 0x98000
	s_addc_u32 s27, s27, 0
	global_load_dwordx4 v[176:179], v165, s[36:37] offset:768
	global_load_dwordx4 v[180:183], v165, s[4:5] offset:768
	s_add_u32 s36, s36, 0x98000
	s_addc_u32 s37, s37, 0
	s_add_u32 s4, s4, 0x98000
	s_addc_u32 s5, s5, 0
	v_exp_f32_e32 v50, v50
	v_exp_f32_e32 v51, v51
	v_exp_f32_e32 v52, v52
	v_exp_f32_e32 v53, v53
	v_exp_f32_e32 v54, v54
	v_exp_f32_e32 v55, v55
	v_exp_f32_e32 v56, v56
	v_exp_f32_e32 v57, v57
	ds_read_b64_tr_b16 v[206:207], v192 offset:0
	ds_read_b64_tr_b16 v[208:209], v192 offset:1536
	ds_read_b64_tr_b16 v[210:211], v192 offset:3072
	ds_read_b64_tr_b16 v[212:213], v192 offset:4608
	v_exp_f32_e32 v58, v58
	v_exp_f32_e32 v59, v59
	v_exp_f32_e32 v60, v60
	v_exp_f32_e32 v61, v61
	v_exp_f32_e32 v62, v62
	v_exp_f32_e32 v63, v63
	v_exp_f32_e32 v64, v64
	v_exp_f32_e32 v65, v65
	ds_read_b64_tr_b16 v[214:215], v192 offset:6144
	ds_read_b64_tr_b16 v[216:217], v192 offset:7680
	ds_read_b64_tr_b16 v[218:219], v192 offset:9216
	s_waitcnt lgkmcnt(14)
	v_mfma_f32_32x32x16_bf16 v[82:97], v[34:37], v[114:117], 0
	v_exp_f32_e32 v66, v66
	v_exp_f32_e32 v67, v67
	v_exp_f32_e32 v68, v68
	s_waitcnt lgkmcnt(13)
	v_mfma_f32_32x32x16_bf16 v[82:97], v[38:41], v[118:121], v[82:97]
	v_exp_f32_e32 v69, v69
	v_exp_f32_e32 v70, v70
	v_exp_f32_e32 v71, v71
	s_waitcnt lgkmcnt(12)
	v_mfma_f32_32x32x16_bf16 v[82:97], v[42:45], v[122:125], v[82:97]
	v_exp_f32_e32 v72, v72
	v_exp_f32_e32 v73, v73
	v_exp_f32_e32 v74, v74
	s_waitcnt lgkmcnt(11)
	v_mfma_f32_32x32x16_bf16 v[82:97], v[46:49], v[126:129], v[82:97]
	v_exp_f32_e32 v75, v75
	v_exp_f32_e32 v76, v76
	v_exp_f32_e32 v77, v77
	s_waitcnt lgkmcnt(10)
	v_mfma_f32_32x32x16_bf16 v[98:113], v[130:133], v[114:117], 0
	v_exp_f32_e32 v78, v78
	v_exp_f32_e32 v79, v79
	v_exp_f32_e32 v80, v80
	s_waitcnt lgkmcnt(9)
	v_mfma_f32_32x32x16_bf16 v[98:113], v[134:137], v[118:121], v[98:113]
	v_exp_f32_e32 v81, v81
	ds_read_b64_tr_b16 v[220:221], v192 offset:10752
	v_cvt_pk_bf16_f32 v146, v50, v51
	v_cvt_pk_bf16_f32 v147, v52, v53
	v_cvt_pk_bf16_f32 v148, v54, v55
	v_cvt_pk_bf16_f32 v149, v56, v57
	s_waitcnt lgkmcnt(9)
	v_mfma_f32_32x32x16_bf16 v[98:113], v[138:141], v[122:125], v[98:113]
	v_cvt_pk_bf16_f32 v150, v58, v59
	v_cvt_pk_bf16_f32 v151, v60, v61
	v_cvt_pk_bf16_f32 v152, v62, v63
	v_cvt_pk_bf16_f32 v153, v64, v65
	v_add_f32_e32 v193, v193, v50
	v_add_f32_e32 v194, v194, v51
	s_waitcnt lgkmcnt(8)
	v_mfma_f32_32x32x16_bf16 v[98:113], v[142:145], v[126:129], v[98:113]
	v_cvt_pk_bf16_f32 v154, v66, v67
	v_cvt_pk_bf16_f32 v155, v68, v69
	s_waitcnt lgkmcnt(6)
	v_mfma_f32_32x32x16_bf16 v[18:33], v[206:209], v[146:149], v[18:33]
	ds_read_b64_tr_b16 v[206:207], v192 offset:64
	ds_read_b64_tr_b16 v[208:209], v192 offset:1600
	v_cvt_pk_bf16_f32 v156, v70, v71
	v_cvt_pk_bf16_f32 v157, v72, v73
	v_add_f32_e32 v195, v195, v52
	v_add_f32_e32 v196, v196, v53
	s_waitcnt lgkmcnt(6)
	v_mfma_f32_32x32x16_bf16 v[18:33], v[210:213], v[150:153], v[18:33]
	ds_read_b64_tr_b16 v[210:211], v192 offset:3136
	ds_read_b64_tr_b16 v[212:213], v192 offset:4672
	v_cvt_pk_bf16_f32 v158, v74, v75
	v_cvt_pk_bf16_f32 v159, v76, v77
	v_add_f32_e32 v193, v193, v54
	v_add_f32_e32 v194, v194, v55
	s_waitcnt lgkmcnt(6)
	v_mfma_f32_32x32x16_bf16 v[18:33], v[214:217], v[154:157], v[18:33]
	ds_read_b64_tr_b16 v[214:215], v192 offset:6208
	ds_read_b64_tr_b16 v[216:217], v192 offset:7744
	v_cvt_pk_bf16_f32 v160, v78, v79
	v_cvt_pk_bf16_f32 v161, v80, v81
	v_add_f32_e32 v195, v195, v56
	v_add_f32_e32 v196, v196, v57
	s_waitcnt lgkmcnt(6)
	v_mfma_f32_32x32x16_bf16 v[18:33], v[218:221], v[158:161], v[18:33]
	ds_read_b64_tr_b16 v[218:219], v192 offset:9280
	ds_read_b64_tr_b16 v[220:221], v192 offset:10816
	v_add_f32_e32 v193, v193, v58
	v_add_f32_e32 v194, v194, v59
	v_add_f32_e32 v195, v195, v60
	v_add_f32_e32 v196, v196, v61
	s_waitcnt lgkmcnt(6)
	v_mfma_f32_32x32x16_bf16 v[2:17], v[206:209], v[146:149], v[2:17]
	v_add_f32_e32 v193, v193, v62
	v_add_f32_e32 v194, v194, v63
	v_add_f32_e32 v195, v195, v64
	v_add_f32_e32 v196, v196, v65
	v_add_f32_e32 v193, v193, v66
	v_add_f32_e32 v194, v194, v67
	s_waitcnt lgkmcnt(4)
	v_mfma_f32_32x32x16_bf16 v[2:17], v[210:213], v[150:153], v[2:17]
	v_add_f32_e32 v195, v195, v68
	v_add_f32_e32 v196, v196, v69
	v_add_f32_e32 v193, v193, v70
	v_add_f32_e32 v194, v194, v71
	v_add_f32_e32 v195, v195, v72
	v_add_f32_e32 v196, v196, v73
	s_waitcnt lgkmcnt(2)
	v_mfma_f32_32x32x16_bf16 v[2:17], v[214:217], v[154:157], v[2:17]
	v_add_f32_e32 v193, v193, v74
	v_add_f32_e32 v194, v194, v75
	v_add_f32_e32 v195, v195, v76
	v_add_f32_e32 v196, v196, v77
	v_add_f32_e32 v193, v193, v78
	v_add_f32_e32 v194, v194, v79
	s_waitcnt lgkmcnt(0)
	v_mfma_f32_32x32x16_bf16 v[2:17], v[218:221], v[158:161], v[2:17]
	v_add_f32_e32 v195, v195, v80
	v_add_f32_e32 v196, v196, v81
	s_waitcnt vmcnt(2)
	s_waitcnt vmcnt(1)
	ds_write_b128 v190, v[176:179] offset:12288
	s_waitcnt vmcnt(0)
	ds_write_b128 v190, v[180:183] offset:18432
	s_waitcnt lgkmcnt(0)
	s_barrier
	ds_read_b128 v[34:37], v191 offset:0
	ds_read_b128 v[38:41], v168 offset:0
	ds_read_b128 v[42:45], v169 offset:0
	ds_read_b128 v[46:49], v170 offset:0
	ds_read_b128 v[130:133], v191 offset:4096
	ds_read_b128 v[134:137], v168 offset:4096
	ds_read_b128 v[138:141], v169 offset:4096
	ds_read_b128 v[142:145], v170 offset:4096
	s_add_u32 m0, m0, 0x2000
	s_nop 0
	global_load_lds_dwordx4 v171, s[26:27]
	s_add_u32 m0, m0, 0x400
	s_nop 0
	global_load_lds_dwordx4 v172, s[26:27]
	s_add_u32 s26, s26, 0x98000
	s_addc_u32 s27, s27, 0
	global_load_dwordx4 v[176:179], v165, s[36:37] offset:768
	global_load_dwordx4 v[180:183], v165, s[4:5] offset:768
	s_add_u32 s36, s36, 0x98000
	s_addc_u32 s37, s37, 0
	s_add_u32 s4, s4, 0x98000
	s_addc_u32 s5, s5, 0
	v_exp_f32_e32 v82, v82
	v_exp_f32_e32 v83, v83
	v_exp_f32_e32 v84, v84
	v_exp_f32_e32 v85, v85
	v_exp_f32_e32 v86, v86
	v_exp_f32_e32 v87, v87
	v_exp_f32_e32 v88, v88
	v_exp_f32_e32 v89, v89
	ds_read_b64_tr_b16 v[206:207], v192 offset:12288
	ds_read_b64_tr_b16 v[208:209], v192 offset:13824
	ds_read_b64_tr_b16 v[210:211], v192 offset:15360
	ds_read_b64_tr_b16 v[212:213], v192 offset:16896
	v_exp_f32_e32 v90, v90
	v_exp_f32_e32 v91, v91
	v_exp_f32_e32 v92, v92
	v_exp_f32_e32 v93, v93
	v_exp_f32_e32 v94, v94
	v_exp_f32_e32 v95, v95
	v_exp_f32_e32 v96, v96
	v_exp_f32_e32 v97, v97
	ds_read_b64_tr_b16 v[214:215], v192 offset:18432
	ds_read_b64_tr_b16 v[216:217], v192 offset:19968
	ds_read_b64_tr_b16 v[218:219], v192 offset:21504
	s_waitcnt lgkmcnt(14)
	v_mfma_f32_32x32x16_bf16 v[50:65], v[34:37], v[114:117], 0
	v_exp_f32_e32 v98, v98
	v_exp_f32_e32 v99, v99
	v_exp_f32_e32 v100, v100
	s_waitcnt lgkmcnt(13)
	v_mfma_f32_32x32x16_bf16 v[50:65], v[38:41], v[118:121], v[50:65]
	v_exp_f32_e32 v101, v101
	v_exp_f32_e32 v102, v102
	v_exp_f32_e32 v103, v103
	s_waitcnt lgkmcnt(12)
	v_mfma_f32_32x32x16_bf16 v[50:65], v[42:45], v[122:125], v[50:65]
	v_exp_f32_e32 v104, v104
	v_exp_f32_e32 v105, v105
	v_exp_f32_e32 v106, v106
	s_waitcnt lgkmcnt(11)
	v_mfma_f32_32x32x16_bf16 v[50:65], v[46:49], v[126:129], v[50:65]
	v_exp_f32_e32 v107, v107
	v_exp_f32_e32 v108, v108
	v_exp_f32_e32 v109, v109
	s_waitcnt lgkmcnt(10)
	v_mfma_f32_32x32x16_bf16 v[66:81], v[130:133], v[114:117], 0
	v_exp_f32_e32 v110, v110
	v_exp_f32_e32 v111, v111
	v_exp_f32_e32 v112, v112
	s_waitcnt lgkmcnt(9)
	v_mfma_f32_32x32x16_bf16 v[66:81], v[134:137], v[118:121], v[66:81]
	v_exp_f32_e32 v113, v113
	ds_read_b64_tr_b16 v[220:221], v192 offset:23040
	v_cvt_pk_bf16_f32 v146, v82, v83
	v_cvt_pk_bf16_f32 v147, v84, v85
	v_cvt_pk_bf16_f32 v148, v86, v87
	v_cvt_pk_bf16_f32 v149, v88, v89
	s_waitcnt lgkmcnt(9)
	v_mfma_f32_32x32x16_bf16 v[66:81], v[138:141], v[122:125], v[66:81]
	v_cvt_pk_bf16_f32 v150, v90, v91
	v_cvt_pk_bf16_f32 v151, v92, v93
	v_cvt_pk_bf16_f32 v152, v94, v95
	v_cvt_pk_bf16_f32 v153, v96, v97
	v_add_f32_e32 v193, v193, v82
	v_add_f32_e32 v194, v194, v83
	s_waitcnt lgkmcnt(8)
	v_mfma_f32_32x32x16_bf16 v[66:81], v[142:145], v[126:129], v[66:81]
	v_cvt_pk_bf16_f32 v154, v98, v99
	v_cvt_pk_bf16_f32 v155, v100, v101
	s_waitcnt lgkmcnt(6)
	v_mfma_f32_32x32x16_bf16 v[18:33], v[206:209], v[146:149], v[18:33]
	ds_read_b64_tr_b16 v[206:207], v192 offset:12352
	ds_read_b64_tr_b16 v[208:209], v192 offset:13888
	v_cvt_pk_bf16_f32 v156, v102, v103
	v_cvt_pk_bf16_f32 v157, v104, v105
	v_add_f32_e32 v195, v195, v84
	v_add_f32_e32 v196, v196, v85
	s_waitcnt lgkmcnt(6)
	v_mfma_f32_32x32x16_bf16 v[18:33], v[210:213], v[150:153], v[18:33]
	ds_read_b64_tr_b16 v[210:211], v192 offset:15424
	ds_read_b64_tr_b16 v[212:213], v192 offset:16960
	v_cvt_pk_bf16_f32 v158, v106, v107
	v_cvt_pk_bf16_f32 v159, v108, v109
	v_add_f32_e32 v193, v193, v86
	v_add_f32_e32 v194, v194, v87
	s_waitcnt lgkmcnt(6)
; template <int DQK, bool FIXEDM>
; DI void attn_dense_mfma(const bf16_t* Qb, int ldq, const bf16_t* Kb, int ldk, const bf16_t* Vb, int ldv, bf16_t* gate_io, char* smem, bool store, float mbound) {
;     ...
;   pc0 = negm; pc1 = negm;
;   STEP(pa0, pa1, pc0, pc1, 0, true, 1, 1);
;   STEP(pc0, pc1, pa0, pa1, 1, false, 1, 1);
;   for (int j = 2; j < NT - 2; j += 2) {
;     STEP(pa0, pa1, pc0, pc1, 0, false, 1, 1);
;     STEP(pc0, pc1, pa0, pa1, 1, false, 1, 1);
;   }
;   STEP(pa0, pa1, pc0, pc1, 0, false, 0, 1);
;   STEP(pc0, pc1, pa0, pa1, 1, false, 0, 0);
	v_mfma_f32_32x32x16_bf16 v[18:33], v[214:217], v[154:157], v[18:33]
	ds_read_b64_tr_b16 v[214:215], v192 offset:18496
	ds_read_b64_tr_b16 v[216:217], v192 offset:20032
	v_cvt_pk_bf16_f32 v160, v110, v111
	v_cvt_pk_bf16_f32 v161, v112, v113
	v_add_f32_e32 v195, v195, v88
	v_add_f32_e32 v196, v196, v89
	s_waitcnt lgkmcnt(6)
	v_mfma_f32_32x32x16_bf16 v[18:33], v[218:221], v[158:161], v[18:33]
	ds_read_b64_tr_b16 v[218:219], v192 offset:21568
	ds_read_b64_tr_b16 v[220:221], v192 offset:23104
	v_add_f32_e32 v193, v193, v90
	v_add_f32_e32 v194, v194, v91
	v_add_f32_e32 v195, v195, v92
	v_add_f32_e32 v196, v196, v93
	s_waitcnt lgkmcnt(6)
	v_mfma_f32_32x32x16_bf16 v[2:17], v[206:209], v[146:149], v[2:17]
	v_add_f32_e32 v193, v193, v94
	v_add_f32_e32 v194, v194, v95
	v_add_f32_e32 v195, v195, v96
	v_add_f32_e32 v196, v196, v97
	v_add_f32_e32 v193, v193, v98
	v_add_f32_e32 v194, v194, v99
	s_waitcnt lgkmcnt(4)
	v_mfma_f32_32x32x16_bf16 v[2:17], v[210:213], v[150:153], v[2:17]
	v_add_f32_e32 v195, v195, v100
	v_add_f32_e32 v196, v196, v101
	v_add_f32_e32 v193, v193, v102
	v_add_f32_e32 v194, v194, v103
	v_add_f32_e32 v195, v195, v104
	v_add_f32_e32 v196, v196, v105
	s_waitcnt lgkmcnt(2)
	v_mfma_f32_32x32x16_bf16 v[2:17], v[214:217], v[154:157], v[2:17]
	v_add_f32_e32 v193, v193, v106
	v_add_f32_e32 v194, v194, v107
	v_add_f32_e32 v195, v195, v108
	v_add_f32_e32 v196, v196, v109
	v_add_f32_e32 v193, v193, v110
	v_add_f32_e32 v194, v194, v111
	s_waitcnt lgkmcnt(0)
	v_mfma_f32_32x32x16_bf16 v[2:17], v[218:221], v[158:161], v[2:17]
	v_add_f32_e32 v195, v195, v112
	v_add_f32_e32 v196, v196, v113
	s_waitcnt vmcnt(2)
	s_waitcnt vmcnt(1)
	ds_write_b128 v190, v[176:179] offset:0
	s_waitcnt vmcnt(0)
	ds_write_b128 v190, v[180:183] offset:6144
	s_waitcnt lgkmcnt(0)
	s_barrier
	s_add_i32 s7, s7, 2
	s_cmpk_lt_u32 s7, 0x7e
	s_cbranch_scc1 .Lattnb_loop
	ds_read_b128 v[34:37], v191 offset:9216
	ds_read_b128 v[38:41], v168 offset:9216
	ds_read_b128 v[42:45], v169 offset:9216
	ds_read_b128 v[46:49], v170 offset:9216
	ds_read_b128 v[130:133], v191 offset:13312
	ds_read_b128 v[134:137], v168 offset:13312
	ds_read_b128 v[138:141], v169 offset:13312
	ds_read_b128 v[142:145], v170 offset:13312
	global_load_dwordx4 v[176:179], v165, s[36:37] offset:768
	global_load_dwordx4 v[180:183], v165, s[4:5] offset:768
	s_add_u32 s36, s36, 0x98000
	s_addc_u32 s37, s37, 0
	s_add_u32 s4, s4, 0x98000
	s_addc_u32 s5, s5, 0
	v_exp_f32_e32 v50, v50
	v_exp_f32_e32 v51, v51
	v_exp_f32_e32 v52, v52
	v_exp_f32_e32 v53, v53
	v_exp_f32_e32 v54, v54
	v_exp_f32_e32 v55, v55
	v_exp_f32_e32 v56, v56
	v_exp_f32_e32 v57, v57
	ds_read_b64_tr_b16 v[206:207], v192 offset:0
	ds_read_b64_tr_b16 v[208:209], v192 offset:1536
	ds_read_b64_tr_b16 v[210:211], v192 offset:3072
	ds_read_b64_tr_b16 v[212:213], v192 offset:4608
	v_exp_f32_e32 v58, v58
	v_exp_f32_e32 v59, v59
	v_exp_f32_e32 v60, v60
	v_exp_f32_e32 v61, v61
	v_exp_f32_e32 v62, v62
	v_exp_f32_e32 v63, v63
	v_exp_f32_e32 v64, v64
	v_exp_f32_e32 v65, v65
	ds_read_b64_tr_b16 v[214:215], v192 offset:6144
	ds_read_b64_tr_b16 v[216:217], v192 offset:7680
	ds_read_b64_tr_b16 v[218:219], v192 offset:9216
	s_waitcnt lgkmcnt(14)
	v_mfma_f32_32x32x16_bf16 v[82:97], v[34:37], v[114:117], 0
	v_exp_f32_e32 v66, v66
	v_exp_f32_e32 v67, v67
	v_exp_f32_e32 v68, v68
	s_waitcnt lgkmcnt(13)
	v_mfma_f32_32x32x16_bf16 v[82:97], v[38:41], v[118:121], v[82:97]
	v_exp_f32_e32 v69, v69
	v_exp_f32_e32 v70, v70
	v_exp_f32_e32 v71, v71
	s_waitcnt lgkmcnt(12)
	v_mfma_f32_32x32x16_bf16 v[82:97], v[42:45], v[122:125], v[82:97]
	v_exp_f32_e32 v72, v72
	v_exp_f32_e32 v73, v73
	v_exp_f32_e32 v74, v74
	s_waitcnt lgkmcnt(11)
	v_mfma_f32_32x32x16_bf16 v[82:97], v[46:49], v[126:129], v[82:97]
	v_exp_f32_e32 v75, v75
	v_exp_f32_e32 v76, v76
	v_exp_f32_e32 v77, v77
	s_waitcnt lgkmcnt(10)
	v_mfma_f32_32x32x16_bf16 v[98:113], v[130:133], v[114:117], 0
	v_exp_f32_e32 v78, v78
	v_exp_f32_e32 v79, v79
	v_exp_f32_e32 v80, v80
	s_waitcnt lgkmcnt(9)
	v_mfma_f32_32x32x16_bf16 v[98:113], v[134:137], v[118:121], v[98:113]
	v_exp_f32_e32 v81, v81
	ds_read_b64_tr_b16 v[220:221], v192 offset:10752
	v_cvt_pk_bf16_f32 v146, v50, v51
	v_cvt_pk_bf16_f32 v147, v52, v53
	v_cvt_pk_bf16_f32 v148, v54, v55
	v_cvt_pk_bf16_f32 v149, v56, v57
	s_waitcnt lgkmcnt(9)
	v_mfma_f32_32x32x16_bf16 v[98:113], v[138:141], v[122:125], v[98:113]
	v_cvt_pk_bf16_f32 v150, v58, v59
	v_cvt_pk_bf16_f32 v151, v60, v61
	v_cvt_pk_bf16_f32 v152, v62, v63
	v_cvt_pk_bf16_f32 v153, v64, v65
	v_add_f32_e32 v193, v193, v50
	v_add_f32_e32 v194, v194, v51
	s_waitcnt lgkmcnt(8)
	v_mfma_f32_32x32x16_bf16 v[98:113], v[142:145], v[126:129], v[98:113]
	v_cvt_pk_bf16_f32 v154, v66, v67
	v_cvt_pk_bf16_f32 v155, v68, v69
	s_waitcnt lgkmcnt(6)
	v_mfma_f32_32x32x16_bf16 v[18:33], v[206:209], v[146:149], v[18:33]
	ds_read_b64_tr_b16 v[206:207], v192 offset:64
	ds_read_b64_tr_b16 v[208:209], v192 offset:1600
	v_cvt_pk_bf16_f32 v156, v70, v71
	v_cvt_pk_bf16_f32 v157, v72, v73
	v_add_f32_e32 v195, v195, v52
	v_add_f32_e32 v196, v196, v53
	s_waitcnt lgkmcnt(6)
	v_mfma_f32_32x32x16_bf16 v[18:33], v[210:213], v[150:153], v[18:33]
	ds_read_b64_tr_b16 v[210:211], v192 offset:3136
	ds_read_b64_tr_b16 v[212:213], v192 offset:4672
	v_cvt_pk_bf16_f32 v158, v74, v75
	v_cvt_pk_bf16_f32 v159, v76, v77
	v_add_f32_e32 v193, v193, v54
	v_add_f32_e32 v194, v194, v55
	s_waitcnt lgkmcnt(6)
	v_mfma_f32_32x32x16_bf16 v[18:33], v[214:217], v[154:157], v[18:33]
	ds_read_b64_tr_b16 v[214:215], v192 offset:6208
	ds_read_b64_tr_b16 v[216:217], v192 offset:7744
	v_cvt_pk_bf16_f32 v160, v78, v79
	v_cvt_pk_bf16_f32 v161, v80, v81
	v_add_f32_e32 v195, v195, v56
	v_add_f32_e32 v196, v196, v57
	s_waitcnt lgkmcnt(6)
; DI float frcp(float x) { return __builtin_amdgcn_rcpf(x); }
; template <int DQK, bool FIXEDM>
; DI void attn_dense_mfma(const bf16_t* Qb, int ldq, const bf16_t* Kb, int ldk, const bf16_t* Vb, int ldv, bf16_t* gate_io, char* smem, bool store, float mbound) {
;     ...
;   STEP(pa0, pa1, pc0, pc1, 0, false, 0, 1);
;   STEP(pc0, pc1, pa0, pa1, 1, false, 0, 0);
;     ...
;   if (!store) return;
;   const float inv = frcp(half_swap_sum(l_run));
	v_mfma_f32_32x32x16_bf16 v[18:33], v[218:221], v[158:161], v[18:33]
	ds_read_b64_tr_b16 v[218:219], v192 offset:9280
	ds_read_b64_tr_b16 v[220:221], v192 offset:10816
	v_add_f32_e32 v193, v193, v58
	v_add_f32_e32 v194, v194, v59
	v_add_f32_e32 v195, v195, v60
	v_add_f32_e32 v196, v196, v61
	s_waitcnt lgkmcnt(6)
	v_mfma_f32_32x32x16_bf16 v[2:17], v[206:209], v[146:149], v[2:17]
	v_add_f32_e32 v193, v193, v62
	v_add_f32_e32 v194, v194, v63
	v_add_f32_e32 v195, v195, v64
	v_add_f32_e32 v196, v196, v65
	v_add_f32_e32 v193, v193, v66
	v_add_f32_e32 v194, v194, v67
	s_waitcnt lgkmcnt(4)
	v_mfma_f32_32x32x16_bf16 v[2:17], v[210:213], v[150:153], v[2:17]
	v_add_f32_e32 v195, v195, v68
	v_add_f32_e32 v196, v196, v69
	v_add_f32_e32 v193, v193, v70
	v_add_f32_e32 v194, v194, v71
	v_add_f32_e32 v195, v195, v72
	v_add_f32_e32 v196, v196, v73
	s_waitcnt lgkmcnt(2)
	v_mfma_f32_32x32x16_bf16 v[2:17], v[214:217], v[154:157], v[2:17]
	v_add_f32_e32 v193, v193, v74
	v_add_f32_e32 v194, v194, v75
	v_add_f32_e32 v195, v195, v76
	v_add_f32_e32 v196, v196, v77
	v_add_f32_e32 v193, v193, v78
	v_add_f32_e32 v194, v194, v79
	s_waitcnt lgkmcnt(0)
	v_mfma_f32_32x32x16_bf16 v[2:17], v[218:221], v[158:161], v[2:17]
	v_add_f32_e32 v195, v195, v80
	v_add_f32_e32 v196, v196, v81
	s_waitcnt vmcnt(1)
	ds_write_b128 v190, v[176:179] offset:12288
	s_waitcnt vmcnt(0)
	ds_write_b128 v190, v[180:183] offset:18432
	s_waitcnt lgkmcnt(0)
	s_barrier
	ds_read_b128 v[34:37], v191 offset:0
	ds_read_b128 v[38:41], v168 offset:0
	ds_read_b128 v[42:45], v169 offset:0
	ds_read_b128 v[46:49], v170 offset:0
	ds_read_b128 v[130:133], v191 offset:4096
	ds_read_b128 v[134:137], v168 offset:4096
	ds_read_b128 v[138:141], v169 offset:4096
	ds_read_b128 v[142:145], v170 offset:4096
	v_exp_f32_e32 v82, v82
	v_exp_f32_e32 v83, v83
	v_exp_f32_e32 v84, v84
	v_exp_f32_e32 v85, v85
	v_exp_f32_e32 v86, v86
	v_exp_f32_e32 v87, v87
	v_exp_f32_e32 v88, v88
	v_exp_f32_e32 v89, v89
	ds_read_b64_tr_b16 v[206:207], v192 offset:12288
	ds_read_b64_tr_b16 v[208:209], v192 offset:13824
	ds_read_b64_tr_b16 v[210:211], v192 offset:15360
	ds_read_b64_tr_b16 v[212:213], v192 offset:16896
	v_exp_f32_e32 v90, v90
	v_exp_f32_e32 v91, v91
	v_exp_f32_e32 v92, v92
	v_exp_f32_e32 v93, v93
	v_exp_f32_e32 v94, v94
	v_exp_f32_e32 v95, v95
	v_exp_f32_e32 v96, v96
	v_exp_f32_e32 v97, v97
	ds_read_b64_tr_b16 v[214:215], v192 offset:18432
	ds_read_b64_tr_b16 v[216:217], v192 offset:19968
	ds_read_b64_tr_b16 v[218:219], v192 offset:21504
	s_waitcnt lgkmcnt(14)
	v_mfma_f32_32x32x16_bf16 v[50:65], v[34:37], v[114:117], 0
	v_exp_f32_e32 v98, v98
	v_exp_f32_e32 v99, v99
	v_exp_f32_e32 v100, v100
	s_waitcnt lgkmcnt(13)
	v_mfma_f32_32x32x16_bf16 v[50:65], v[38:41], v[118:121], v[50:65]
	v_exp_f32_e32 v101, v101
	v_exp_f32_e32 v102, v102
	v_exp_f32_e32 v103, v103
	s_waitcnt lgkmcnt(12)
	v_mfma_f32_32x32x16_bf16 v[50:65], v[42:45], v[122:125], v[50:65]
	v_exp_f32_e32 v104, v104
	v_exp_f32_e32 v105, v105
	v_exp_f32_e32 v106, v106
	s_waitcnt lgkmcnt(11)
	v_mfma_f32_32x32x16_bf16 v[50:65], v[46:49], v[126:129], v[50:65]
	v_exp_f32_e32 v107, v107
	v_exp_f32_e32 v108, v108
	v_exp_f32_e32 v109, v109
	s_waitcnt lgkmcnt(10)
	v_mfma_f32_32x32x16_bf16 v[66:81], v[130:133], v[114:117], 0
	v_exp_f32_e32 v110, v110
	v_exp_f32_e32 v111, v111
	v_exp_f32_e32 v112, v112
	s_waitcnt lgkmcnt(9)
	v_mfma_f32_32x32x16_bf16 v[66:81], v[134:137], v[118:121], v[66:81]
	v_exp_f32_e32 v113, v113
	ds_read_b64_tr_b16 v[220:221], v192 offset:23040
	v_cvt_pk_bf16_f32 v146, v82, v83
	v_cvt_pk_bf16_f32 v147, v84, v85
	v_cvt_pk_bf16_f32 v148, v86, v87
	v_cvt_pk_bf16_f32 v149, v88, v89
	s_waitcnt lgkmcnt(9)
	v_mfma_f32_32x32x16_bf16 v[66:81], v[138:141], v[122:125], v[66:81]
	v_cvt_pk_bf16_f32 v150, v90, v91
	v_cvt_pk_bf16_f32 v151, v92, v93
	v_cvt_pk_bf16_f32 v152, v94, v95
	v_cvt_pk_bf16_f32 v153, v96, v97
	v_add_f32_e32 v193, v193, v82
	v_add_f32_e32 v194, v194, v83
	s_waitcnt lgkmcnt(8)
	v_mfma_f32_32x32x16_bf16 v[66:81], v[142:145], v[126:129], v[66:81]
	v_cvt_pk_bf16_f32 v154, v98, v99
	v_cvt_pk_bf16_f32 v155, v100, v101
	s_waitcnt lgkmcnt(6)
	v_mfma_f32_32x32x16_bf16 v[18:33], v[206:209], v[146:149], v[18:33]
	ds_read_b64_tr_b16 v[206:207], v192 offset:12352
	ds_read_b64_tr_b16 v[208:209], v192 offset:13888
	v_cvt_pk_bf16_f32 v156, v102, v103
	v_cvt_pk_bf16_f32 v157, v104, v105
	v_add_f32_e32 v195, v195, v84
	v_add_f32_e32 v196, v196, v85
	s_waitcnt lgkmcnt(6)
	v_mfma_f32_32x32x16_bf16 v[18:33], v[210:213], v[150:153], v[18:33]
	ds_read_b64_tr_b16 v[210:211], v192 offset:15424
	ds_read_b64_tr_b16 v[212:213], v192 offset:16960
	v_cvt_pk_bf16_f32 v158, v106, v107
	v_cvt_pk_bf16_f32 v159, v108, v109
	v_add_f32_e32 v193, v193, v86
	v_add_f32_e32 v194, v194, v87
	s_waitcnt lgkmcnt(6)
	v_mfma_f32_32x32x16_bf16 v[18:33], v[214:217], v[154:157], v[18:33]
	ds_read_b64_tr_b16 v[214:215], v192 offset:18496
	ds_read_b64_tr_b16 v[216:217], v192 offset:20032
	v_cvt_pk_bf16_f32 v160, v110, v111
	v_cvt_pk_bf16_f32 v161, v112, v113
	v_add_f32_e32 v195, v195, v88
	v_add_f32_e32 v196, v196, v89
	s_waitcnt lgkmcnt(6)
	v_mfma_f32_32x32x16_bf16 v[18:33], v[218:221], v[158:161], v[18:33]
	ds_read_b64_tr_b16 v[218:219], v192 offset:21568
	ds_read_b64_tr_b16 v[220:221], v192 offset:23104
	v_add_f32_e32 v193, v193, v90
	v_add_f32_e32 v194, v194, v91
	v_add_f32_e32 v195, v195, v92
	v_add_f32_e32 v196, v196, v93
	s_waitcnt lgkmcnt(6)
	v_mfma_f32_32x32x16_bf16 v[2:17], v[206:209], v[146:149], v[2:17]
	v_add_f32_e32 v193, v193, v94
	v_add_f32_e32 v194, v194, v95
	v_add_f32_e32 v195, v195, v96
	v_add_f32_e32 v196, v196, v97
	v_add_f32_e32 v193, v193, v98
	v_add_f32_e32 v194, v194, v99
	s_waitcnt lgkmcnt(4)
	v_mfma_f32_32x32x16_bf16 v[2:17], v[210:213], v[150:153], v[2:17]
	v_add_f32_e32 v195, v195, v100
	v_add_f32_e32 v196, v196, v101
	v_add_f32_e32 v193, v193, v102
	v_add_f32_e32 v194, v194, v103
	v_add_f32_e32 v195, v195, v104
	v_add_f32_e32 v196, v196, v105
	s_waitcnt lgkmcnt(2)
	v_mfma_f32_32x32x16_bf16 v[2:17], v[214:217], v[154:157], v[2:17]
	v_add_f32_e32 v193, v193, v106
	v_add_f32_e32 v194, v194, v107
	v_add_f32_e32 v195, v195, v108
	v_add_f32_e32 v196, v196, v109
	v_add_f32_e32 v193, v193, v110
	v_add_f32_e32 v194, v194, v111
	s_waitcnt lgkmcnt(0)
	v_mfma_f32_32x32x16_bf16 v[2:17], v[218:221], v[158:161], v[2:17]
	v_add_f32_e32 v195, v195, v112
	v_add_f32_e32 v196, v196, v113
	s_barrier
	v_add_f32_e32 v193, v193, v194
	v_add_f32_e32 v195, v195, v196
	v_add_f32_e32 v0, v193, v195
	v_mov_b32_e32 v34, v0
	s_nop 1
	v_permlane32_swap_b32_e32 v0, v34
	v_add_f32_e32 v0, v0, v34
	v_rcp_f32_e32 v34, v0
	s_movk_i32 s11, 0x2000
	v_mov_b32_e32 v190, 0x358637bd
	v_xor_b32_e32 v191, 16, v204
	v_xor_b32_e32 v192, 8, v204
	v_xor_b32_e32 v193, 4, v204
	v_xor_b32_e32 v194, 2, v204
	v_xor_b32_e32 v195, 1, v204
	s_nop 3
